# merge epilogue de-serialised: gate / pass-1 partial loads issued 4 rows ahead with counted vmcnt waits and one dwordx4 store per row (was load-wait-store per row)
# speedup vs baseline: 1.0640x; 1.0066x over previous
.LBB0_430:
	s_or_b64 exec, exec, s[6:7]
	s_xor_b64 s[6:7], s[8:9], -1
	v_lshl_add_u32 v192, s10, 7, v170
	s_mov_b32 s10, 0
	s_waitcnt lgkmcnt(0)
	s_barrier
	s_mov_b64 s[62:63], 0x10000
	s_mov_b64 s[64:65], 0x8000
	v_lshlrev_b64 v[172:173], 12, v[192:193]
	v_lshlrev_b64 v[174:175], 11, v[192:193]
	v_lshl_add_u64 v[172:173], v[150:151], 0, v[172:173]
	s_and_b64 vcc, exec, s[4:5]
	s_cbranch_vccz .Lmrg_pass0
	v_lshl_add_u64 v[204:205], v[132:133], 0, v[174:175]
	v_lshl_add_u64 v[174:175], v[130:131], 0, v[174:175]
	global_load_dwordx4 v[176:179], v[172:173], off
	v_lshl_add_u64 v[172:173], v[172:173], 0, s[62:63]
	global_load_dwordx4 v[200:203], v[174:175], off
	v_lshl_add_u64 v[174:175], v[174:175], 0, s[64:65]
	global_load_dwordx4 v[180:183], v[172:173], off
	v_lshl_add_u64 v[172:173], v[172:173], 0, s[62:63]
	global_load_dwordx4 v[212:215], v[174:175], off
	v_lshl_add_u64 v[174:175], v[174:175], 0, s[64:65]
	global_load_dwordx4 v[184:187], v[172:173], off
	v_lshl_add_u64 v[172:173], v[172:173], 0, s[62:63]
	global_load_dwordx4 v[216:219], v[174:175], off
	v_lshl_add_u64 v[174:175], v[174:175], 0, s[64:65]
	global_load_dwordx4 v[196:199], v[172:173], off
	v_lshl_add_u64 v[172:173], v[172:173], 0, s[62:63]
	global_load_dwordx4 v[240:243], v[174:175], off
	v_lshl_add_u64 v[174:175], v[174:175], 0, s[64:65]
	ds_read_b128 v[152:155], v171
	ds_read_b128 v[160:163], v171 offset:16
	s_waitcnt vmcnt(6)
	v_lshlrev_b32_e32 v220, 16, v176
	v_and_b32_e32 v221, 0xffff0000, v176
	v_lshlrev_b32_e32 v222, 16, v177
	v_and_b32_e32 v234, 0xffff0000, v177
	v_lshlrev_b32_e32 v239, 16, v178
	v_and_b32_e32 v248, 0xffff0000, v178
	v_lshlrev_b32_e32 v249, 16, v179
	v_and_b32_e32 v250, 0xffff0000, v179
	s_waitcnt lgkmcnt(0)
	v_mul_f32_e32 v152, v152, v220
	v_mul_f32_e32 v153, v153, v221
	v_mul_f32_e32 v154, v154, v222
	v_mul_f32_e32 v155, v155, v234
	v_mul_f32_e32 v160, v160, v239
	v_mul_f32_e32 v161, v161, v248
	v_mul_f32_e32 v162, v162, v249
	v_mul_f32_e32 v163, v163, v250
	v_lshlrev_b32_e32 v220, 16, v200
	v_and_b32_e32 v221, 0xffff0000, v200
	v_lshlrev_b32_e32 v222, 16, v201
	v_and_b32_e32 v234, 0xffff0000, v201
	v_lshlrev_b32_e32 v239, 16, v202
	v_and_b32_e32 v248, 0xffff0000, v202
	v_lshlrev_b32_e32 v249, 16, v203
	v_and_b32_e32 v250, 0xffff0000, v203
	v_add_f32_e32 v152, v152, v220
	v_add_f32_e32 v153, v153, v221
	v_add_f32_e32 v154, v154, v222
	v_add_f32_e32 v155, v155, v234
	v_add_f32_e32 v160, v160, v239
	v_add_f32_e32 v161, v161, v248
	v_add_f32_e32 v162, v162, v249
	v_add_f32_e32 v163, v163, v250
	v_cvt_pk_bf16_f32 v156, v152, v153
	v_cvt_pk_bf16_f32 v157, v154, v155
	v_cvt_pk_bf16_f32 v158, v160, v161
	v_cvt_pk_bf16_f32 v159, v162, v163
	global_store_dwordx4 v[204:205], v[156:159], off
	v_lshl_add_u64 v[204:205], v[204:205], 0, s[64:65]
	ds_read_b128 v[152:155], v171 offset:8448
	ds_read_b128 v[160:163], v171 offset:8464
	s_waitcnt vmcnt(5)
	v_lshlrev_b32_e32 v220, 16, v180
	v_and_b32_e32 v221, 0xffff0000, v180
	v_lshlrev_b32_e32 v222, 16, v181
	v_and_b32_e32 v234, 0xffff0000, v181
	v_lshlrev_b32_e32 v239, 16, v182
	v_and_b32_e32 v248, 0xffff0000, v182
	v_lshlrev_b32_e32 v249, 16, v183
	v_and_b32_e32 v250, 0xffff0000, v183
	s_waitcnt lgkmcnt(0)
	v_mul_f32_e32 v152, v152, v220
	v_mul_f32_e32 v153, v153, v221
	v_mul_f32_e32 v154, v154, v222
	v_mul_f32_e32 v155, v155, v234
	v_mul_f32_e32 v160, v160, v239
	v_mul_f32_e32 v161, v161, v248
	v_mul_f32_e32 v162, v162, v249
	v_mul_f32_e32 v163, v163, v250
	v_lshlrev_b32_e32 v220, 16, v212
	v_and_b32_e32 v221, 0xffff0000, v212
	v_lshlrev_b32_e32 v222, 16, v213
	v_and_b32_e32 v234, 0xffff0000, v213
	v_lshlrev_b32_e32 v239, 16, v214
	v_and_b32_e32 v248, 0xffff0000, v214
	v_lshlrev_b32_e32 v249, 16, v215
	v_and_b32_e32 v250, 0xffff0000, v215
	v_add_f32_e32 v152, v152, v220
	v_add_f32_e32 v153, v153, v221
	v_add_f32_e32 v154, v154, v222
	v_add_f32_e32 v155, v155, v234
	v_add_f32_e32 v160, v160, v239
	v_add_f32_e32 v161, v161, v248
	v_add_f32_e32 v162, v162, v249
	v_add_f32_e32 v163, v163, v250
	v_cvt_pk_bf16_f32 v156, v152, v153
	v_cvt_pk_bf16_f32 v157, v154, v155
	v_cvt_pk_bf16_f32 v158, v160, v161
	v_cvt_pk_bf16_f32 v159, v162, v163
	global_store_dwordx4 v[204:205], v[156:159], off
	v_lshl_add_u64 v[204:205], v[204:205], 0, s[64:65]
	ds_read_b128 v[152:155], v171 offset:16896
	ds_read_b128 v[160:163], v171 offset:16912
	s_waitcnt vmcnt(4)
	v_lshlrev_b32_e32 v220, 16, v184
	v_and_b32_e32 v221, 0xffff0000, v184
	v_lshlrev_b32_e32 v222, 16, v185
	v_and_b32_e32 v234, 0xffff0000, v185
	v_lshlrev_b32_e32 v239, 16, v186
	v_and_b32_e32 v248, 0xffff0000, v186
	v_lshlrev_b32_e32 v249, 16, v187
	v_and_b32_e32 v250, 0xffff0000, v187
	s_waitcnt lgkmcnt(0)
	v_mul_f32_e32 v152, v152, v220
	v_mul_f32_e32 v153, v153, v221
	v_mul_f32_e32 v154, v154, v222
	v_mul_f32_e32 v155, v155, v234
	v_mul_f32_e32 v160, v160, v239
	v_mul_f32_e32 v161, v161, v248
	v_mul_f32_e32 v162, v162, v249
	v_mul_f32_e32 v163, v163, v250
	v_lshlrev_b32_e32 v220, 16, v216
	v_and_b32_e32 v221, 0xffff0000, v216
	v_lshlrev_b32_e32 v222, 16, v217
	v_and_b32_e32 v234, 0xffff0000, v217
	v_lshlrev_b32_e32 v239, 16, v218
	v_and_b32_e32 v248, 0xffff0000, v218
	v_lshlrev_b32_e32 v249, 16, v219
	v_and_b32_e32 v250, 0xffff0000, v219
	v_add_f32_e32 v152, v152, v220
	v_add_f32_e32 v153, v153, v221
	v_add_f32_e32 v154, v154, v222
	v_add_f32_e32 v155, v155, v234
	v_add_f32_e32 v160, v160, v239
	v_add_f32_e32 v161, v161, v248
	v_add_f32_e32 v162, v162, v249
	v_add_f32_e32 v163, v163, v250
	v_cvt_pk_bf16_f32 v156, v152, v153
	v_cvt_pk_bf16_f32 v157, v154, v155
	v_cvt_pk_bf16_f32 v158, v160, v161
	v_cvt_pk_bf16_f32 v159, v162, v163
	global_store_dwordx4 v[204:205], v[156:159], off
	v_lshl_add_u64 v[204:205], v[204:205], 0, s[64:65]
	ds_read_b128 v[152:155], v171 offset:25344
	ds_read_b128 v[160:163], v171 offset:25360
	s_waitcnt vmcnt(3)
	v_lshlrev_b32_e32 v220, 16, v196
	v_and_b32_e32 v221, 0xffff0000, v196
	v_lshlrev_b32_e32 v222, 16, v197
	v_and_b32_e32 v234, 0xffff0000, v197
	v_lshlrev_b32_e32 v239, 16, v198
	v_and_b32_e32 v248, 0xffff0000, v198
	v_lshlrev_b32_e32 v249, 16, v199
	v_and_b32_e32 v250, 0xffff0000, v199
	s_waitcnt lgkmcnt(0)
	v_mul_f32_e32 v152, v152, v220
	v_mul_f32_e32 v153, v153, v221
	v_mul_f32_e32 v154, v154, v222
	v_mul_f32_e32 v155, v155, v234
	v_mul_f32_e32 v160, v160, v239
	v_mul_f32_e32 v161, v161, v248
	v_mul_f32_e32 v162, v162, v249
	v_mul_f32_e32 v163, v163, v250
	v_lshlrev_b32_e32 v220, 16, v240
	v_and_b32_e32 v221, 0xffff0000, v240
	v_lshlrev_b32_e32 v222, 16, v241
	v_and_b32_e32 v234, 0xffff0000, v241
	v_lshlrev_b32_e32 v239, 16, v242
	v_and_b32_e32 v248, 0xffff0000, v242
	v_lshlrev_b32_e32 v249, 16, v243
	v_and_b32_e32 v250, 0xffff0000, v243
	v_add_f32_e32 v152, v152, v220
	v_add_f32_e32 v153, v153, v221
	v_add_f32_e32 v154, v154, v222
	v_add_f32_e32 v155, v155, v234
	v_add_f32_e32 v160, v160, v239
	v_add_f32_e32 v161, v161, v248
	v_add_f32_e32 v162, v162, v249
	v_add_f32_e32 v163, v163, v250
	v_cvt_pk_bf16_f32 v156, v152, v153
	v_cvt_pk_bf16_f32 v157, v154, v155
	v_cvt_pk_bf16_f32 v158, v160, v161
	v_cvt_pk_bf16_f32 v159, v162, v163
	global_store_dwordx4 v[204:205], v[156:159], off
	v_lshl_add_u64 v[204:205], v[204:205], 0, s[64:65]
	global_load_dwordx4 v[176:179], v[172:173], off
	v_lshl_add_u64 v[172:173], v[172:173], 0, s[62:63]
	global_load_dwordx4 v[200:203], v[174:175], off
	v_lshl_add_u64 v[174:175], v[174:175], 0, s[64:65]
	global_load_dwordx4 v[180:183], v[172:173], off
	v_lshl_add_u64 v[172:173], v[172:173], 0, s[62:63]
	global_load_dwordx4 v[212:215], v[174:175], off
	v_lshl_add_u64 v[174:175], v[174:175], 0, s[64:65]
	global_load_dwordx4 v[184:187], v[172:173], off
	v_lshl_add_u64 v[172:173], v[172:173], 0, s[62:63]
	global_load_dwordx4 v[216:219], v[174:175], off
	v_lshl_add_u64 v[174:175], v[174:175], 0, s[64:65]
	global_load_dwordx4 v[196:199], v[172:173], off
	v_lshl_add_u64 v[172:173], v[172:173], 0, s[62:63]
	global_load_dwordx4 v[240:243], v[174:175], off
	v_lshl_add_u64 v[174:175], v[174:175], 0, s[64:65]
	ds_read_b128 v[152:155], v171 offset:33792
	ds_read_b128 v[160:163], v171 offset:33808
	s_waitcnt vmcnt(6)
	v_lshlrev_b32_e32 v220, 16, v176
	v_and_b32_e32 v221, 0xffff0000, v176
	v_lshlrev_b32_e32 v222, 16, v177
	v_and_b32_e32 v234, 0xffff0000, v177
	v_lshlrev_b32_e32 v239, 16, v178
	v_and_b32_e32 v248, 0xffff0000, v178
	v_lshlrev_b32_e32 v249, 16, v179
	v_and_b32_e32 v250, 0xffff0000, v179
	s_waitcnt lgkmcnt(0)
	v_mul_f32_e32 v152, v152, v220
	v_mul_f32_e32 v153, v153, v221
	v_mul_f32_e32 v154, v154, v222
	v_mul_f32_e32 v155, v155, v234
	v_mul_f32_e32 v160, v160, v239
	v_mul_f32_e32 v161, v161, v248
	v_mul_f32_e32 v162, v162, v249
	v_mul_f32_e32 v163, v163, v250
	v_lshlrev_b32_e32 v220, 16, v200
	v_and_b32_e32 v221, 0xffff0000, v200
	v_lshlrev_b32_e32 v222, 16, v201
	v_and_b32_e32 v234, 0xffff0000, v201
	v_lshlrev_b32_e32 v239, 16, v202
	v_and_b32_e32 v248, 0xffff0000, v202
	v_lshlrev_b32_e32 v249, 16, v203
	v_and_b32_e32 v250, 0xffff0000, v203
	v_add_f32_e32 v152, v152, v220
	v_add_f32_e32 v153, v153, v221
	v_add_f32_e32 v154, v154, v222
	v_add_f32_e32 v155, v155, v234
	v_add_f32_e32 v160, v160, v239
	v_add_f32_e32 v161, v161, v248
	v_add_f32_e32 v162, v162, v249
	v_add_f32_e32 v163, v163, v250
	v_cvt_pk_bf16_f32 v156, v152, v153
	v_cvt_pk_bf16_f32 v157, v154, v155
	v_cvt_pk_bf16_f32 v158, v160, v161
	v_cvt_pk_bf16_f32 v159, v162, v163
	global_store_dwordx4 v[204:205], v[156:159], off
	v_lshl_add_u64 v[204:205], v[204:205], 0, s[64:65]
	ds_read_b128 v[152:155], v171 offset:42240
	ds_read_b128 v[160:163], v171 offset:42256
	s_waitcnt vmcnt(5)
	v_lshlrev_b32_e32 v220, 16, v180
	v_and_b32_e32 v221, 0xffff0000, v180
	v_lshlrev_b32_e32 v222, 16, v181
	v_and_b32_e32 v234, 0xffff0000, v181
	v_lshlrev_b32_e32 v239, 16, v182
	v_and_b32_e32 v248, 0xffff0000, v182
	v_lshlrev_b32_e32 v249, 16, v183
	v_and_b32_e32 v250, 0xffff0000, v183
	s_waitcnt lgkmcnt(0)
	v_mul_f32_e32 v152, v152, v220
	v_mul_f32_e32 v153, v153, v221
	v_mul_f32_e32 v154, v154, v222
	v_mul_f32_e32 v155, v155, v234
	v_mul_f32_e32 v160, v160, v239
	v_mul_f32_e32 v161, v161, v248
	v_mul_f32_e32 v162, v162, v249
	v_mul_f32_e32 v163, v163, v250
	v_lshlrev_b32_e32 v220, 16, v212
	v_and_b32_e32 v221, 0xffff0000, v212
	v_lshlrev_b32_e32 v222, 16, v213
	v_and_b32_e32 v234, 0xffff0000, v213
	v_lshlrev_b32_e32 v239, 16, v214
	v_and_b32_e32 v248, 0xffff0000, v214
	v_lshlrev_b32_e32 v249, 16, v215
	v_and_b32_e32 v250, 0xffff0000, v215
	v_add_f32_e32 v152, v152, v220
	v_add_f32_e32 v153, v153, v221
	v_add_f32_e32 v154, v154, v222
	v_add_f32_e32 v155, v155, v234
	v_add_f32_e32 v160, v160, v239
	v_add_f32_e32 v161, v161, v248
	v_add_f32_e32 v162, v162, v249
	v_add_f32_e32 v163, v163, v250
	v_cvt_pk_bf16_f32 v156, v152, v153
	v_cvt_pk_bf16_f32 v157, v154, v155
	v_cvt_pk_bf16_f32 v158, v160, v161
	v_cvt_pk_bf16_f32 v159, v162, v163
	global_store_dwordx4 v[204:205], v[156:159], off
	v_lshl_add_u64 v[204:205], v[204:205], 0, s[64:65]
	ds_read_b128 v[152:155], v171 offset:50688
	ds_read_b128 v[160:163], v171 offset:50704
	s_waitcnt vmcnt(4)
	v_lshlrev_b32_e32 v220, 16, v184
	v_and_b32_e32 v221, 0xffff0000, v184
	v_lshlrev_b32_e32 v222, 16, v185
	v_and_b32_e32 v234, 0xffff0000, v185
	v_lshlrev_b32_e32 v239, 16, v186
	v_and_b32_e32 v248, 0xffff0000, v186
	v_lshlrev_b32_e32 v249, 16, v187
	v_and_b32_e32 v250, 0xffff0000, v187
	s_waitcnt lgkmcnt(0)
	v_mul_f32_e32 v152, v152, v220
	v_mul_f32_e32 v153, v153, v221
	v_mul_f32_e32 v154, v154, v222
	v_mul_f32_e32 v155, v155, v234
	v_mul_f32_e32 v160, v160, v239
	v_mul_f32_e32 v161, v161, v248
	v_mul_f32_e32 v162, v162, v249
	v_mul_f32_e32 v163, v163, v250
	v_lshlrev_b32_e32 v220, 16, v216
	v_and_b32_e32 v221, 0xffff0000, v216
	v_lshlrev_b32_e32 v222, 16, v217
	v_and_b32_e32 v234, 0xffff0000, v217
	v_lshlrev_b32_e32 v239, 16, v218
	v_and_b32_e32 v248, 0xffff0000, v218
	v_lshlrev_b32_e32 v249, 16, v219
	v_and_b32_e32 v250, 0xffff0000, v219
	v_add_f32_e32 v152, v152, v220
	v_add_f32_e32 v153, v153, v221
	v_add_f32_e32 v154, v154, v222
	v_add_f32_e32 v155, v155, v234
	v_add_f32_e32 v160, v160, v239
	v_add_f32_e32 v161, v161, v248
	v_add_f32_e32 v162, v162, v249
	v_add_f32_e32 v163, v163, v250
	v_cvt_pk_bf16_f32 v156, v152, v153
	v_cvt_pk_bf16_f32 v157, v154, v155
	v_cvt_pk_bf16_f32 v158, v160, v161
	v_cvt_pk_bf16_f32 v159, v162, v163
	global_store_dwordx4 v[204:205], v[156:159], off
	v_lshl_add_u64 v[204:205], v[204:205], 0, s[64:65]
	ds_read_b128 v[152:155], v171 offset:59136
	ds_read_b128 v[160:163], v171 offset:59152
	s_waitcnt vmcnt(3)
	v_lshlrev_b32_e32 v220, 16, v196
	v_and_b32_e32 v221, 0xffff0000, v196
	v_lshlrev_b32_e32 v222, 16, v197
	v_and_b32_e32 v234, 0xffff0000, v197
	v_lshlrev_b32_e32 v239, 16, v198
	v_and_b32_e32 v248, 0xffff0000, v198
	v_lshlrev_b32_e32 v249, 16, v199
	v_and_b32_e32 v250, 0xffff0000, v199
	s_waitcnt lgkmcnt(0)
	v_mul_f32_e32 v152, v152, v220
	v_mul_f32_e32 v153, v153, v221
	v_mul_f32_e32 v154, v154, v222
	v_mul_f32_e32 v155, v155, v234
	v_mul_f32_e32 v160, v160, v239
	v_mul_f32_e32 v161, v161, v248
	v_mul_f32_e32 v162, v162, v249
	v_mul_f32_e32 v163, v163, v250
	v_lshlrev_b32_e32 v220, 16, v240
	v_and_b32_e32 v221, 0xffff0000, v240
	v_lshlrev_b32_e32 v222, 16, v241
	v_and_b32_e32 v234, 0xffff0000, v241
	v_lshlrev_b32_e32 v239, 16, v242
	v_and_b32_e32 v248, 0xffff0000, v242
	v_lshlrev_b32_e32 v249, 16, v243
	v_and_b32_e32 v250, 0xffff0000, v243
	v_add_f32_e32 v152, v152, v220
	v_add_f32_e32 v153, v153, v221
	v_add_f32_e32 v154, v154, v222
	v_add_f32_e32 v155, v155, v234
	v_add_f32_e32 v160, v160, v239
	v_add_f32_e32 v161, v161, v248
	v_add_f32_e32 v162, v162, v249
	v_add_f32_e32 v163, v163, v250
	v_cvt_pk_bf16_f32 v156, v152, v153
	v_cvt_pk_bf16_f32 v157, v154, v155
	v_cvt_pk_bf16_f32 v158, v160, v161
	v_cvt_pk_bf16_f32 v159, v162, v163
	global_store_dwordx4 v[204:205], v[156:159], off
	v_lshl_add_u64 v[204:205], v[204:205], 0, s[64:65]
	s_branch .LBB0_427
.Lmrg_pass0:
	v_lshl_add_u64 v[204:205], v[130:131], 0, v[174:175]
	global_load_dwordx4 v[176:179], v[172:173], off
	v_lshl_add_u64 v[172:173], v[172:173], 0, s[62:63]
	global_load_dwordx4 v[180:183], v[172:173], off
	v_lshl_add_u64 v[172:173], v[172:173], 0, s[62:63]
	global_load_dwordx4 v[184:187], v[172:173], off
	v_lshl_add_u64 v[172:173], v[172:173], 0, s[62:63]
	global_load_dwordx4 v[196:199], v[172:173], off
	v_lshl_add_u64 v[172:173], v[172:173], 0, s[62:63]
	ds_read_b128 v[152:155], v171
	ds_read_b128 v[160:163], v171 offset:16
	s_waitcnt vmcnt(3)
	v_lshlrev_b32_e32 v220, 16, v176
	v_and_b32_e32 v221, 0xffff0000, v176
	v_lshlrev_b32_e32 v222, 16, v177
	v_and_b32_e32 v234, 0xffff0000, v177
	v_lshlrev_b32_e32 v239, 16, v178
	v_and_b32_e32 v248, 0xffff0000, v178
	v_lshlrev_b32_e32 v249, 16, v179
	v_and_b32_e32 v250, 0xffff0000, v179
	s_waitcnt lgkmcnt(0)
	v_mul_f32_e32 v152, v152, v220
	v_mul_f32_e32 v153, v153, v221
	v_mul_f32_e32 v154, v154, v222
	v_mul_f32_e32 v155, v155, v234
	v_mul_f32_e32 v160, v160, v239
	v_mul_f32_e32 v161, v161, v248
	v_mul_f32_e32 v162, v162, v249
	v_mul_f32_e32 v163, v163, v250
	v_cvt_pk_bf16_f32 v156, v152, v153
	v_cvt_pk_bf16_f32 v157, v154, v155
	v_cvt_pk_bf16_f32 v158, v160, v161
	v_cvt_pk_bf16_f32 v159, v162, v163
	global_store_dwordx4 v[204:205], v[156:159], off
	v_lshl_add_u64 v[204:205], v[204:205], 0, s[64:65]
	ds_read_b128 v[152:155], v171 offset:8448
	ds_read_b128 v[160:163], v171 offset:8464
	s_waitcnt vmcnt(3)
	v_lshlrev_b32_e32 v220, 16, v180
	v_and_b32_e32 v221, 0xffff0000, v180
	v_lshlrev_b32_e32 v222, 16, v181
	v_and_b32_e32 v234, 0xffff0000, v181
	v_lshlrev_b32_e32 v239, 16, v182
	v_and_b32_e32 v248, 0xffff0000, v182
	v_lshlrev_b32_e32 v249, 16, v183
	v_and_b32_e32 v250, 0xffff0000, v183
	s_waitcnt lgkmcnt(0)
	v_mul_f32_e32 v152, v152, v220
	v_mul_f32_e32 v153, v153, v221
	v_mul_f32_e32 v154, v154, v222
	v_mul_f32_e32 v155, v155, v234
	v_mul_f32_e32 v160, v160, v239
	v_mul_f32_e32 v161, v161, v248
	v_mul_f32_e32 v162, v162, v249
	v_mul_f32_e32 v163, v163, v250
	v_cvt_pk_bf16_f32 v156, v152, v153
	v_cvt_pk_bf16_f32 v157, v154, v155
	v_cvt_pk_bf16_f32 v158, v160, v161
	v_cvt_pk_bf16_f32 v159, v162, v163
	global_store_dwordx4 v[204:205], v[156:159], off
	v_lshl_add_u64 v[204:205], v[204:205], 0, s[64:65]
	ds_read_b128 v[152:155], v171 offset:16896
	ds_read_b128 v[160:163], v171 offset:16912
	s_waitcnt vmcnt(3)
	v_lshlrev_b32_e32 v220, 16, v184
	v_and_b32_e32 v221, 0xffff0000, v184
	v_lshlrev_b32_e32 v222, 16, v185
	v_and_b32_e32 v234, 0xffff0000, v185
	v_lshlrev_b32_e32 v239, 16, v186
	v_and_b32_e32 v248, 0xffff0000, v186
	v_lshlrev_b32_e32 v249, 16, v187
	v_and_b32_e32 v250, 0xffff0000, v187
	s_waitcnt lgkmcnt(0)
	v_mul_f32_e32 v152, v152, v220
	v_mul_f32_e32 v153, v153, v221
	v_mul_f32_e32 v154, v154, v222
	v_mul_f32_e32 v155, v155, v234
	v_mul_f32_e32 v160, v160, v239
	v_mul_f32_e32 v161, v161, v248
	v_mul_f32_e32 v162, v162, v249
	v_mul_f32_e32 v163, v163, v250
	v_cvt_pk_bf16_f32 v156, v152, v153
	v_cvt_pk_bf16_f32 v157, v154, v155
	v_cvt_pk_bf16_f32 v158, v160, v161
	v_cvt_pk_bf16_f32 v159, v162, v163
	global_store_dwordx4 v[204:205], v[156:159], off
	v_lshl_add_u64 v[204:205], v[204:205], 0, s[64:65]
	ds_read_b128 v[152:155], v171 offset:25344
	ds_read_b128 v[160:163], v171 offset:25360
	s_waitcnt vmcnt(3)
	v_lshlrev_b32_e32 v220, 16, v196
	v_and_b32_e32 v221, 0xffff0000, v196
	v_lshlrev_b32_e32 v222, 16, v197
	v_and_b32_e32 v234, 0xffff0000, v197
	v_lshlrev_b32_e32 v239, 16, v198
	v_and_b32_e32 v248, 0xffff0000, v198
	v_lshlrev_b32_e32 v249, 16, v199
	v_and_b32_e32 v250, 0xffff0000, v199
	s_waitcnt lgkmcnt(0)
	v_mul_f32_e32 v152, v152, v220
	v_mul_f32_e32 v153, v153, v221
	v_mul_f32_e32 v154, v154, v222
	v_mul_f32_e32 v155, v155, v234
	v_mul_f32_e32 v160, v160, v239
	v_mul_f32_e32 v161, v161, v248
	v_mul_f32_e32 v162, v162, v249
	v_mul_f32_e32 v163, v163, v250
	v_cvt_pk_bf16_f32 v156, v152, v153
	v_cvt_pk_bf16_f32 v157, v154, v155
	v_cvt_pk_bf16_f32 v158, v160, v161
	v_cvt_pk_bf16_f32 v159, v162, v163
	global_store_dwordx4 v[204:205], v[156:159], off
	v_lshl_add_u64 v[204:205], v[204:205], 0, s[64:65]
	global_load_dwordx4 v[176:179], v[172:173], off
	v_lshl_add_u64 v[172:173], v[172:173], 0, s[62:63]
	global_load_dwordx4 v[180:183], v[172:173], off
	v_lshl_add_u64 v[172:173], v[172:173], 0, s[62:63]
	global_load_dwordx4 v[184:187], v[172:173], off
	v_lshl_add_u64 v[172:173], v[172:173], 0, s[62:63]
	global_load_dwordx4 v[196:199], v[172:173], off
	v_lshl_add_u64 v[172:173], v[172:173], 0, s[62:63]
	ds_read_b128 v[152:155], v171 offset:33792
	ds_read_b128 v[160:163], v171 offset:33808
	s_waitcnt vmcnt(3)
	v_lshlrev_b32_e32 v220, 16, v176
	v_and_b32_e32 v221, 0xffff0000, v176
	v_lshlrev_b32_e32 v222, 16, v177
	v_and_b32_e32 v234, 0xffff0000, v177
	v_lshlrev_b32_e32 v239, 16, v178
	v_and_b32_e32 v248, 0xffff0000, v178
	v_lshlrev_b32_e32 v249, 16, v179
	v_and_b32_e32 v250, 0xffff0000, v179
	s_waitcnt lgkmcnt(0)
	v_mul_f32_e32 v152, v152, v220
	v_mul_f32_e32 v153, v153, v221
	v_mul_f32_e32 v154, v154, v222
	v_mul_f32_e32 v155, v155, v234
	v_mul_f32_e32 v160, v160, v239
	v_mul_f32_e32 v161, v161, v248
	v_mul_f32_e32 v162, v162, v249
	v_mul_f32_e32 v163, v163, v250
	v_cvt_pk_bf16_f32 v156, v152, v153
	v_cvt_pk_bf16_f32 v157, v154, v155
	v_cvt_pk_bf16_f32 v158, v160, v161
	v_cvt_pk_bf16_f32 v159, v162, v163
	global_store_dwordx4 v[204:205], v[156:159], off
	v_lshl_add_u64 v[204:205], v[204:205], 0, s[64:65]
	ds_read_b128 v[152:155], v171 offset:42240
	ds_read_b128 v[160:163], v171 offset:42256
	s_waitcnt vmcnt(3)
	v_lshlrev_b32_e32 v220, 16, v180
	v_and_b32_e32 v221, 0xffff0000, v180
	v_lshlrev_b32_e32 v222, 16, v181
	v_and_b32_e32 v234, 0xffff0000, v181
	v_lshlrev_b32_e32 v239, 16, v182
	v_and_b32_e32 v248, 0xffff0000, v182
	v_lshlrev_b32_e32 v249, 16, v183
	v_and_b32_e32 v250, 0xffff0000, v183
	s_waitcnt lgkmcnt(0)
	v_mul_f32_e32 v152, v152, v220
	v_mul_f32_e32 v153, v153, v221
	v_mul_f32_e32 v154, v154, v222
	v_mul_f32_e32 v155, v155, v234
	v_mul_f32_e32 v160, v160, v239
	v_mul_f32_e32 v161, v161, v248
	v_mul_f32_e32 v162, v162, v249
	v_mul_f32_e32 v163, v163, v250
	v_cvt_pk_bf16_f32 v156, v152, v153
	v_cvt_pk_bf16_f32 v157, v154, v155
	v_cvt_pk_bf16_f32 v158, v160, v161
	v_cvt_pk_bf16_f32 v159, v162, v163
	global_store_dwordx4 v[204:205], v[156:159], off
	v_lshl_add_u64 v[204:205], v[204:205], 0, s[64:65]
	ds_read_b128 v[152:155], v171 offset:50688
	ds_read_b128 v[160:163], v171 offset:50704
	s_waitcnt vmcnt(3)
	v_lshlrev_b32_e32 v220, 16, v184
	v_and_b32_e32 v221, 0xffff0000, v184
	v_lshlrev_b32_e32 v222, 16, v185
	v_and_b32_e32 v234, 0xffff0000, v185
	v_lshlrev_b32_e32 v239, 16, v186
	v_and_b32_e32 v248, 0xffff0000, v186
	v_lshlrev_b32_e32 v249, 16, v187
	v_and_b32_e32 v250, 0xffff0000, v187
	s_waitcnt lgkmcnt(0)
	v_mul_f32_e32 v152, v152, v220
	v_mul_f32_e32 v153, v153, v221
	v_mul_f32_e32 v154, v154, v222
	v_mul_f32_e32 v155, v155, v234
	v_mul_f32_e32 v160, v160, v239
	v_mul_f32_e32 v161, v161, v248
	v_mul_f32_e32 v162, v162, v249
	v_mul_f32_e32 v163, v163, v250
	v_cvt_pk_bf16_f32 v156, v152, v153
	v_cvt_pk_bf16_f32 v157, v154, v155
	v_cvt_pk_bf16_f32 v158, v160, v161
	v_cvt_pk_bf16_f32 v159, v162, v163
	global_store_dwordx4 v[204:205], v[156:159], off
	v_lshl_add_u64 v[204:205], v[204:205], 0, s[64:65]
	ds_read_b128 v[152:155], v171 offset:59136
	ds_read_b128 v[160:163], v171 offset:59152
	s_waitcnt vmcnt(3)
	v_lshlrev_b32_e32 v220, 16, v196
	v_and_b32_e32 v221, 0xffff0000, v196
	v_lshlrev_b32_e32 v222, 16, v197
	v_and_b32_e32 v234, 0xffff0000, v197
	v_lshlrev_b32_e32 v239, 16, v198
	v_and_b32_e32 v248, 0xffff0000, v198
	v_lshlrev_b32_e32 v249, 16, v199
	v_and_b32_e32 v250, 0xffff0000, v199
	s_waitcnt lgkmcnt(0)
	v_mul_f32_e32 v152, v152, v220
	v_mul_f32_e32 v153, v153, v221
	v_mul_f32_e32 v154, v154, v222
	v_mul_f32_e32 v155, v155, v234
	v_mul_f32_e32 v160, v160, v239
	v_mul_f32_e32 v161, v161, v248
	v_mul_f32_e32 v162, v162, v249
	v_mul_f32_e32 v163, v163, v250
	v_cvt_pk_bf16_f32 v156, v152, v153
	v_cvt_pk_bf16_f32 v157, v154, v155
	v_cvt_pk_bf16_f32 v158, v160, v161
	v_cvt_pk_bf16_f32 v159, v162, v163
	global_store_dwordx4 v[204:205], v[156:159], off
	v_lshl_add_u64 v[204:205], v[204:205], 0, s[64:65]
	s_branch .LBB0_427
